# as v29 plus accumulator zeroing between GEMM units done with 64-bit moves
# speedup vs baseline: 1.0140x; 1.0063x over previous
; template <class Epi, bool ALIGN_EPI>
; __device__ __forceinline__ void gemm_phase(LAS unsigned char* lds, const Gemm g, const StaticOrder S, const Epi E) {
;     ...
;     for (;;) {
;         const bool has_next = S.next(ui + 1, nxt);
;         const char* nA = has_next ? (const char*)g.A + (size_t)nxt.pm * tstepA + PG8_KOFS(nxt) : cA; const char* nB = has_next ? (const char*)g.Bt + (size_t)nxt.pn * tstepB + PG8_KOFS(nxt) : cB;
;     ...
; #pragma unroll
;         for (int a = 0; a < 2; ++a)
; #pragma unroll
;             for (int b = 0; b < 2; ++b)
; #pragma unroll
;                 for (int m = 0; m < 4; ++m)
; #pragma unroll
;                     for (int n = 0; n < 2; ++n) acc[a][b][m][n] = (f32x4){0.f, 0.f, 0.f, 0.f};
.LBB0_603:
	s_ashr_i32 s67, s66, 31
	s_lshl_b64 s[0:1], s[66:67], 19
	s_add_u32 s68, s94, s0
	s_addc_u32 s69, s95, s1
	s_and_b64 s[0:1], s[42:43], exec
	s_cselect_b32 s34, s69, s49
	s_cselect_b32 s35, s68, s48
	s_ashr_i32 s65, s64, 31
	s_lshl_b64 s[0:1], s[64:65], 19
	s_add_u32 s70, s58, s0
	s_addc_u32 s71, s72, s1
	s_and_b64 s[0:1], s[42:43], exec
	s_cselect_b32 s50, s71, s47
	s_cselect_b32 s51, s70, s46
	s_add_u32 s40, s48, 0x40080
	s_addc_u32 s41, s49, 0
	s_add_u32 s52, s46, 0x100
	v_mov_b32_e32 v0, 0
	s_addc_u32 s53, s47, 0
	s_mov_b32 s54, -2
	v_mov_b32_e32 v1, 0
	v_mov_b64_e32 v[2:3], 0
	v_mov_b64_e32 v[4:5], 0
	v_mov_b64_e32 v[6:7], 0
	v_mov_b64_e32 v[8:9], 0
	v_mov_b64_e32 v[10:11], 0
	v_mov_b64_e32 v[12:13], 0
	v_mov_b64_e32 v[14:15], 0
	v_mov_b64_e32 v[16:17], 0
	v_mov_b64_e32 v[18:19], 0
	v_mov_b64_e32 v[20:21], 0
	v_mov_b64_e32 v[22:23], 0
	v_mov_b64_e32 v[24:25], 0
	v_mov_b64_e32 v[26:27], 0
	v_mov_b64_e32 v[28:29], 0
	v_mov_b64_e32 v[30:31], 0
	v_mov_b64_e32 v[32:33], 0
	v_mov_b64_e32 v[34:35], 0
	v_mov_b64_e32 v[36:37], 0
	v_mov_b64_e32 v[38:39], 0
	v_mov_b64_e32 v[40:41], 0
	v_mov_b64_e32 v[42:43], 0
	v_mov_b64_e32 v[44:45], 0
	v_mov_b64_e32 v[46:47], 0
	v_mov_b64_e32 v[48:49], 0
	v_mov_b64_e32 v[50:51], 0
	v_mov_b64_e32 v[52:53], 0
	v_mov_b64_e32 v[54:55], 0
	v_mov_b64_e32 v[56:57], 0
	v_mov_b64_e32 v[58:59], 0
	v_mov_b64_e32 v[60:61], 0
	v_mov_b64_e32 v[62:63], 0
	v_mov_b64_e32 v[64:65], 0
	v_mov_b64_e32 v[66:67], 0
	v_mov_b64_e32 v[68:69], 0
	v_mov_b64_e32 v[70:71], 0
	v_mov_b64_e32 v[72:73], 0
	v_mov_b64_e32 v[74:75], 0
	v_mov_b64_e32 v[76:77], 0
	v_mov_b64_e32 v[78:79], 0
	v_mov_b64_e32 v[82:83], 0
	v_mov_b64_e32 v[84:85], 0
	v_mov_b64_e32 v[86:87], 0
	v_mov_b64_e32 v[88:89], 0
	v_mov_b64_e32 v[90:91], 0
	v_mov_b64_e32 v[92:93], 0
	v_mov_b64_e32 v[94:95], 0
	v_mov_b64_e32 v[96:97], 0
	v_mov_b64_e32 v[98:99], 0
	v_mov_b64_e32 v[100:101], 0
	v_mov_b64_e32 v[102:103], 0
	v_mov_b64_e32 v[104:105], 0
	v_mov_b64_e32 v[106:107], 0
	v_mov_b64_e32 v[108:109], 0
	v_mov_b64_e32 v[110:111], 0
	v_mov_b64_e32 v[112:113], 0
	v_mov_b64_e32 v[114:115], 0
	v_mov_b64_e32 v[116:117], 0
	v_mov_b64_e32 v[118:119], 0
	v_mov_b64_e32 v[120:121], 0
	v_mov_b64_e32 v[122:123], 0
	v_mov_b64_e32 v[124:125], 0
	v_mov_b64_e32 v[126:127], 0
	v_mov_b64_e32 v[128:129], 0

; template <class Epi, bool ALIGN_EPI>
; __device__ __forceinline__ void gemm_phase(LAS unsigned char* lds, const Gemm g, const StaticOrder S, const Epi E) {
;     ...
; #pragma unroll
;         for (int a = 0; a < 2; ++a)
; #pragma unroll
;             for (int b = 0; b < 2; ++b)
; #pragma unroll
;                 for (int m = 0; m < 4; ++m)
; #pragma unroll
;                     for (int n = 0; n < 2; ++n) acc[a][b][m][n] = (f32x4){0.f, 0.f, 0.f, 0.f};
.LBB0_727:
	s_add_u32 s28, s50, 0x100
	v_mov_b32_e32 v0, 0
	s_addc_u32 s29, s51, 0
	s_mov_b32 s30, -2
	v_mov_b32_e32 v1, 0
	v_mov_b64_e32 v[2:3], 0
	v_mov_b64_e32 v[4:5], 0
	v_mov_b64_e32 v[6:7], 0
	v_mov_b64_e32 v[8:9], 0
	v_mov_b64_e32 v[10:11], 0
	v_mov_b64_e32 v[12:13], 0
	v_mov_b64_e32 v[14:15], 0
	v_mov_b64_e32 v[16:17], 0
	v_mov_b64_e32 v[18:19], 0
	v_mov_b64_e32 v[20:21], 0
	v_mov_b64_e32 v[22:23], 0
	v_mov_b64_e32 v[24:25], 0
	v_mov_b64_e32 v[26:27], 0
	v_mov_b64_e32 v[28:29], 0
	v_mov_b64_e32 v[30:31], 0
	v_mov_b64_e32 v[32:33], 0
	v_mov_b64_e32 v[34:35], 0
	v_mov_b64_e32 v[36:37], 0
	v_mov_b64_e32 v[38:39], 0
	v_mov_b64_e32 v[40:41], 0
	v_mov_b64_e32 v[42:43], 0
	v_mov_b64_e32 v[44:45], 0
	v_mov_b64_e32 v[46:47], 0
	v_mov_b64_e32 v[48:49], 0
	v_mov_b64_e32 v[50:51], 0
	v_mov_b64_e32 v[52:53], 0
	v_mov_b64_e32 v[54:55], 0
	v_mov_b64_e32 v[56:57], 0
	v_mov_b64_e32 v[58:59], 0
	v_mov_b64_e32 v[60:61], 0
	v_mov_b64_e32 v[62:63], 0
	v_mov_b64_e32 v[64:65], 0
	v_mov_b64_e32 v[66:67], 0
	v_mov_b64_e32 v[68:69], 0
	v_mov_b64_e32 v[70:71], 0
	v_mov_b64_e32 v[72:73], 0
	v_mov_b64_e32 v[74:75], 0
	v_mov_b64_e32 v[76:77], 0
	v_mov_b64_e32 v[78:79], 0
	v_mov_b64_e32 v[82:83], 0
	v_mov_b64_e32 v[84:85], 0
	v_mov_b64_e32 v[86:87], 0
	v_mov_b64_e32 v[88:89], 0
	v_mov_b64_e32 v[90:91], 0
	v_mov_b64_e32 v[92:93], 0
	v_mov_b64_e32 v[94:95], 0
	v_mov_b64_e32 v[96:97], 0
	v_mov_b64_e32 v[98:99], 0
	v_mov_b64_e32 v[100:101], 0
	v_mov_b64_e32 v[102:103], 0
	v_mov_b64_e32 v[104:105], 0
	v_mov_b64_e32 v[106:107], 0
	v_mov_b64_e32 v[108:109], 0
	v_mov_b64_e32 v[110:111], 0
	v_mov_b64_e32 v[112:113], 0
	v_mov_b64_e32 v[114:115], 0
	v_mov_b64_e32 v[116:117], 0
	v_mov_b64_e32 v[118:119], 0
	v_mov_b64_e32 v[120:121], 0
	v_mov_b64_e32 v[122:123], 0
	v_mov_b64_e32 v[124:125], 0
	v_mov_b64_e32 v[126:127], 0
	v_mov_b64_e32 v[128:129], 0

; template <class Epi, bool ALIGN_EPI>
; __device__ __forceinline__ void gemm_phase(LAS unsigned char* lds, const Gemm g, const StaticOrder S, const Epi E) {
;     ...
;     for (;;) {
;         const bool has_next = S.next(ui + 1, nxt);
;         const char* nA = has_next ? (const char*)g.A + (size_t)nxt.pm * tstepA + PG8_KOFS(nxt) : cA; const char* nB = has_next ? (const char*)g.Bt + (size_t)nxt.pn * tstepB + PG8_KOFS(nxt) : cB;
;     ...
; #pragma unroll
;         for (int a = 0; a < 2; ++a)
; #pragma unroll
;             for (int b = 0; b < 2; ++b)
; #pragma unroll
;                 for (int m = 0; m < 4; ++m)
; #pragma unroll
;                     for (int n = 0; n < 2; ++n) acc[a][b][m][n] = (f32x4){0.f, 0.f, 0.f, 0.f};
.LBB0_852:
	s_ashr_i32 s53, s52, 31
	s_lshl_b64 s[0:1], s[52:53], 19
	s_add_u32 s62, s94, s0
	s_addc_u32 s63, s95, s1
	s_and_b64 s[0:1], s[42:43], exec
	s_cselect_b32 s34, s63, s67
	s_cselect_b32 s35, s62, s66
	s_ashr_i32 s51, s50, 31
	s_lshl_b64 s[0:1], s[50:51], 19
	v_readlane_b32 s2, v255, 14
	s_add_u32 s64, s2, s0
	v_readlane_b32 s0, v255, 15
	s_addc_u32 s65, s0, s1
	s_and_b64 s[0:1], s[42:43], exec
	s_cselect_b32 s51, s65, s45
	s_cselect_b32 s53, s64, s44
	s_add_u32 s2, s66, 0x40080
	s_addc_u32 s3, s67, 0
	s_add_u32 s58, s44, 0x100
	v_mov_b32_e32 v0, 0
	s_addc_u32 s61, s45, 0
	s_mov_b32 s68, -2
	v_mov_b32_e32 v1, 0
	v_mov_b64_e32 v[2:3], 0
	v_mov_b64_e32 v[4:5], 0
	v_mov_b64_e32 v[6:7], 0
	v_mov_b64_e32 v[8:9], 0
	v_mov_b64_e32 v[10:11], 0
	v_mov_b64_e32 v[12:13], 0
	v_mov_b64_e32 v[14:15], 0
	v_mov_b64_e32 v[16:17], 0
	v_mov_b64_e32 v[18:19], 0
	v_mov_b64_e32 v[20:21], 0
	v_mov_b64_e32 v[22:23], 0
	v_mov_b64_e32 v[24:25], 0
	v_mov_b64_e32 v[26:27], 0
	v_mov_b64_e32 v[28:29], 0
	v_mov_b64_e32 v[30:31], 0
	v_mov_b64_e32 v[32:33], 0
	v_mov_b64_e32 v[34:35], 0
	v_mov_b64_e32 v[36:37], 0
	v_mov_b64_e32 v[38:39], 0
	v_mov_b64_e32 v[40:41], 0
	v_mov_b64_e32 v[42:43], 0
	v_mov_b64_e32 v[44:45], 0
	v_mov_b64_e32 v[46:47], 0
	v_mov_b64_e32 v[48:49], 0
	v_mov_b64_e32 v[50:51], 0
	v_mov_b64_e32 v[52:53], 0
	v_mov_b64_e32 v[54:55], 0
	v_mov_b64_e32 v[56:57], 0
	v_mov_b64_e32 v[58:59], 0
	v_mov_b64_e32 v[60:61], 0
	v_mov_b64_e32 v[62:63], 0
	v_mov_b64_e32 v[64:65], 0
	v_mov_b64_e32 v[66:67], 0
	v_mov_b64_e32 v[68:69], 0
	v_mov_b64_e32 v[70:71], 0
	v_mov_b64_e32 v[72:73], 0
	v_mov_b64_e32 v[74:75], 0
	v_mov_b64_e32 v[76:77], 0
	v_mov_b64_e32 v[78:79], 0
	v_mov_b64_e32 v[82:83], 0
	v_mov_b64_e32 v[84:85], 0
	v_mov_b64_e32 v[86:87], 0
	v_mov_b64_e32 v[88:89], 0
	v_mov_b64_e32 v[90:91], 0
	v_mov_b64_e32 v[92:93], 0
	v_mov_b64_e32 v[94:95], 0
	v_mov_b64_e32 v[96:97], 0
	v_mov_b64_e32 v[98:99], 0
	v_mov_b64_e32 v[100:101], 0
	v_mov_b64_e32 v[102:103], 0
	v_mov_b64_e32 v[104:105], 0
	v_mov_b64_e32 v[106:107], 0
	v_mov_b64_e32 v[108:109], 0
	v_mov_b64_e32 v[110:111], 0
	v_mov_b64_e32 v[112:113], 0
	v_mov_b64_e32 v[114:115], 0
	v_mov_b64_e32 v[116:117], 0
	v_mov_b64_e32 v[118:119], 0
	v_mov_b64_e32 v[120:121], 0
	v_mov_b64_e32 v[122:123], 0
	v_mov_b64_e32 v[124:125], 0
	v_mov_b64_e32 v[126:127], 0
	v_mov_b64_e32 v[128:129], 0

; template <class Epi, bool ALIGN_EPI>
; __device__ __forceinline__ void gemm_phase(LAS unsigned char* lds, const Gemm g, const StaticOrder S, const Epi E) {
;     ...
;     for (;;) {
;         const bool has_next = S.next(ui + 1, nxt);
;         const char* nA = has_next ? (const char*)g.A + (size_t)nxt.pm * tstepA + PG8_KOFS(nxt) : cA; const char* nB = has_next ? (const char*)g.Bt + (size_t)nxt.pn * tstepB + PG8_KOFS(nxt) : cB;
;     ...
; #pragma unroll
;         for (int a = 0; a < 2; ++a)
; #pragma unroll
;             for (int b = 0; b < 2; ++b)
; #pragma unroll
;                 for (int m = 0; m < 4; ++m)
; #pragma unroll
;                     for (int n = 0; n < 2; ++n) acc[a][b][m][n] = (f32x4){0.f, 0.f, 0.f, 0.f};
.LBB0_1430:
	s_ashr_i32 s49, s48, 31
	s_lshl_b64 s[0:1], s[48:49], 19
	v_readlane_b32 s12, v255, 29
	s_add_u32 s52, s12, s0
	v_readlane_b32 s0, v255, 30
	s_addc_u32 s53, s0, s1
	s_and_b64 s[0:1], s[44:45], exec
	s_cselect_b32 s34, s53, s65
	s_cselect_b32 s35, s52, s64
	s_add_u32 s49, s64, 0x100
	v_mov_b32_e32 v0, 0
	s_addc_u32 s55, s65, 0
	s_mov_b32 s71, -2
	v_mov_b32_e32 v1, 0
	v_mov_b64_e32 v[2:3], 0
	v_mov_b64_e32 v[4:5], 0
	v_mov_b64_e32 v[6:7], 0
	v_mov_b64_e32 v[8:9], 0
	v_mov_b64_e32 v[10:11], 0
	v_mov_b64_e32 v[12:13], 0
	v_mov_b64_e32 v[14:15], 0
	v_mov_b64_e32 v[16:17], 0
	v_mov_b64_e32 v[18:19], 0
	v_mov_b64_e32 v[20:21], 0
	v_mov_b64_e32 v[22:23], 0
	v_mov_b64_e32 v[24:25], 0
	v_mov_b64_e32 v[26:27], 0
	v_mov_b64_e32 v[28:29], 0
	v_mov_b64_e32 v[30:31], 0
	v_mov_b64_e32 v[32:33], 0
	v_mov_b64_e32 v[34:35], 0
	v_mov_b64_e32 v[36:37], 0
	v_mov_b64_e32 v[38:39], 0
	v_mov_b64_e32 v[40:41], 0
	v_mov_b64_e32 v[42:43], 0
	v_mov_b64_e32 v[44:45], 0
	v_mov_b64_e32 v[46:47], 0
	v_mov_b64_e32 v[48:49], 0
	v_mov_b64_e32 v[50:51], 0
	v_mov_b64_e32 v[52:53], 0
	v_mov_b64_e32 v[54:55], 0
	v_mov_b64_e32 v[56:57], 0
	v_mov_b64_e32 v[58:59], 0
	v_mov_b64_e32 v[60:61], 0
	v_mov_b64_e32 v[62:63], 0
	v_mov_b64_e32 v[64:65], 0
	v_mov_b64_e32 v[66:67], 0
	v_mov_b64_e32 v[68:69], 0
	v_mov_b64_e32 v[70:71], 0
	v_mov_b64_e32 v[72:73], 0
	v_mov_b64_e32 v[74:75], 0
	v_mov_b64_e32 v[76:77], 0
	v_mov_b64_e32 v[78:79], 0
	v_mov_b64_e32 v[82:83], 0
	v_mov_b64_e32 v[84:85], 0
	v_mov_b64_e32 v[86:87], 0
	v_mov_b64_e32 v[88:89], 0
	v_mov_b64_e32 v[90:91], 0
	v_mov_b64_e32 v[92:93], 0
	v_mov_b64_e32 v[94:95], 0
	v_mov_b64_e32 v[96:97], 0
	v_mov_b64_e32 v[98:99], 0
	v_mov_b64_e32 v[100:101], 0
	v_mov_b64_e32 v[102:103], 0
	v_mov_b64_e32 v[104:105], 0
	v_mov_b64_e32 v[106:107], 0
	v_mov_b64_e32 v[108:109], 0
	v_mov_b64_e32 v[110:111], 0
	v_mov_b64_e32 v[112:113], 0
	v_mov_b64_e32 v[114:115], 0
	v_mov_b64_e32 v[116:117], 0
	v_mov_b64_e32 v[118:119], 0
	v_mov_b64_e32 v[120:121], 0
	v_mov_b64_e32 v[122:123], 0
	v_mov_b64_e32 v[124:125], 0
	v_mov_b64_e32 v[126:127], 0
	v_mov_b64_e32 v[128:129], 0

; template <class Epi, bool ALIGN_EPI>
; __device__ __forceinline__ void gemm_phase(LAS unsigned char* lds, const Gemm g, const StaticOrder S, const Epi E) {
;     ...
;     for (;;) {
;         const bool has_next = S.next(ui + 1, nxt);
;         const char* nA = has_next ? (const char*)g.A + (size_t)nxt.pm * tstepA + PG8_KOFS(nxt) : cA; const char* nB = has_next ? (const char*)g.Bt + (size_t)nxt.pn * tstepB + PG8_KOFS(nxt) : cB;
;     ...
; #pragma unroll
;         for (int a = 0; a < 2; ++a)
; #pragma unroll
;             for (int b = 0; b < 2; ++b)
; #pragma unroll
;                 for (int m = 0; m < 4; ++m)
; #pragma unroll
;                     for (int n = 0; n < 2; ++n) acc[a][b][m][n] = (f32x4){0.f, 0.f, 0.f, 0.f};
.LBB0_1554:
	s_ashr_i32 s51, s50, 31
	s_lshl_b64 s[0:1], s[50:51], 19
	s_add_u32 s54, s94, s0
	s_addc_u32 s55, s95, s1
	s_and_b64 s[0:1], s[40:41], exec
	s_cselect_b32 s34, s55, s65
	s_cselect_b32 s35, s54, s64
	s_ashr_i32 s49, s48, 31
	s_lshl_b64 s[0:1], s[48:49], 19
	v_readlane_b32 s2, v255, 31
	s_add_u32 s62, s2, s0
	v_readlane_b32 s0, v255, 32
	s_addc_u32 s63, s0, s1
	s_and_b64 s[0:1], s[40:41], exec
	s_cselect_b32 s49, s63, s43
	s_cselect_b32 s51, s62, s42
	s_add_u32 s2, s64, 0x40080
	s_addc_u32 s3, s65, 0
	s_add_u32 s66, s42, 0x100
	v_mov_b32_e32 v0, 0
	s_addc_u32 s67, s43, 0
	s_mov_b32 s68, -2
	v_mov_b32_e32 v1, 0
	v_mov_b64_e32 v[2:3], 0
	v_mov_b64_e32 v[4:5], 0
	v_mov_b64_e32 v[6:7], 0
	v_mov_b64_e32 v[8:9], 0
	v_mov_b64_e32 v[10:11], 0
	v_mov_b64_e32 v[12:13], 0
	v_mov_b64_e32 v[14:15], 0
	v_mov_b64_e32 v[16:17], 0
	v_mov_b64_e32 v[18:19], 0
	v_mov_b64_e32 v[20:21], 0
	v_mov_b64_e32 v[22:23], 0
	v_mov_b64_e32 v[24:25], 0
	v_mov_b64_e32 v[26:27], 0
	v_mov_b64_e32 v[28:29], 0
	v_mov_b64_e32 v[30:31], 0
	v_mov_b64_e32 v[32:33], 0
	v_mov_b64_e32 v[34:35], 0
	v_mov_b64_e32 v[36:37], 0
	v_mov_b64_e32 v[38:39], 0
	v_mov_b64_e32 v[40:41], 0
	v_mov_b64_e32 v[42:43], 0
	v_mov_b64_e32 v[44:45], 0
	v_mov_b64_e32 v[46:47], 0
	v_mov_b64_e32 v[48:49], 0
	v_mov_b64_e32 v[50:51], 0
	v_mov_b64_e32 v[52:53], 0
	v_mov_b64_e32 v[54:55], 0
	v_mov_b64_e32 v[56:57], 0
	v_mov_b64_e32 v[58:59], 0
	v_mov_b64_e32 v[60:61], 0
	v_mov_b64_e32 v[62:63], 0
	v_mov_b64_e32 v[64:65], 0
	v_mov_b64_e32 v[66:67], 0
	v_mov_b64_e32 v[68:69], 0
	v_mov_b64_e32 v[70:71], 0
	v_mov_b64_e32 v[72:73], 0
	v_mov_b64_e32 v[74:75], 0
	v_mov_b64_e32 v[76:77], 0
	v_mov_b64_e32 v[78:79], 0
	v_mov_b64_e32 v[82:83], 0
	v_mov_b64_e32 v[84:85], 0
	v_mov_b64_e32 v[86:87], 0
	v_mov_b64_e32 v[88:89], 0
	v_mov_b64_e32 v[90:91], 0
	v_mov_b64_e32 v[92:93], 0
	v_mov_b64_e32 v[94:95], 0
	v_mov_b64_e32 v[96:97], 0
	v_mov_b64_e32 v[98:99], 0
	v_mov_b64_e32 v[100:101], 0
	v_mov_b64_e32 v[102:103], 0
	v_mov_b64_e32 v[104:105], 0
	v_mov_b64_e32 v[106:107], 0
	v_mov_b64_e32 v[108:109], 0
	v_mov_b64_e32 v[110:111], 0
	v_mov_b64_e32 v[112:113], 0
	v_mov_b64_e32 v[114:115], 0
	v_mov_b64_e32 v[116:117], 0
	v_mov_b64_e32 v[118:119], 0
	v_mov_b64_e32 v[120:121], 0
	v_mov_b64_e32 v[122:123], 0
	v_mov_b64_e32 v[124:125], 0
	v_mov_b64_e32 v[126:127], 0
	v_mov_b64_e32 v[128:129], 0

; template <class Epi, bool ALIGN_EPI>
; __device__ __forceinline__ void gemm_phase(LAS unsigned char* lds, const Gemm g, const StaticOrder S, const Epi E) {
;     ...
; #pragma unroll
;         for (int a = 0; a < 2; ++a)
; #pragma unroll
;             for (int b = 0; b < 2; ++b)
; #pragma unroll
;                 for (int m = 0; m < 4; ++m)
; #pragma unroll
;                     for (int n = 0; n < 2; ++n) acc[a][b][m][n] = (f32x4){0.f, 0.f, 0.f, 0.f};
.LBB0_1756:
	s_add_u32 s26, s50, 0x100
	v_mov_b32_e32 v0, 0
	s_addc_u32 s27, s51, 0
	s_mov_b32 s28, -2
	v_mov_b32_e32 v1, 0
	v_mov_b64_e32 v[2:3], 0
	v_mov_b64_e32 v[4:5], 0
	v_mov_b64_e32 v[6:7], 0
	v_mov_b64_e32 v[8:9], 0
	v_mov_b64_e32 v[10:11], 0
	v_mov_b64_e32 v[12:13], 0
	v_mov_b64_e32 v[14:15], 0
	v_mov_b64_e32 v[16:17], 0
	v_mov_b64_e32 v[18:19], 0
	v_mov_b64_e32 v[20:21], 0
	v_mov_b64_e32 v[22:23], 0
	v_mov_b64_e32 v[24:25], 0
	v_mov_b64_e32 v[26:27], 0
	v_mov_b64_e32 v[28:29], 0
	v_mov_b64_e32 v[30:31], 0
	v_mov_b64_e32 v[32:33], 0
	v_mov_b64_e32 v[34:35], 0
	v_mov_b64_e32 v[36:37], 0
	v_mov_b64_e32 v[38:39], 0
	v_mov_b64_e32 v[40:41], 0
	v_mov_b64_e32 v[42:43], 0
	v_mov_b64_e32 v[44:45], 0
	v_mov_b64_e32 v[46:47], 0
	v_mov_b64_e32 v[48:49], 0
	v_mov_b64_e32 v[50:51], 0
	v_mov_b64_e32 v[52:53], 0
	v_mov_b64_e32 v[54:55], 0
	v_mov_b64_e32 v[56:57], 0
	v_mov_b64_e32 v[58:59], 0
	v_mov_b64_e32 v[60:61], 0
	v_mov_b64_e32 v[62:63], 0
	v_mov_b64_e32 v[64:65], 0
	v_mov_b64_e32 v[66:67], 0
	v_mov_b64_e32 v[68:69], 0
	v_mov_b64_e32 v[70:71], 0
	v_mov_b64_e32 v[72:73], 0
	v_mov_b64_e32 v[74:75], 0
	v_mov_b64_e32 v[76:77], 0
	v_mov_b64_e32 v[78:79], 0
	v_mov_b64_e32 v[82:83], 0
	v_mov_b64_e32 v[84:85], 0
	v_mov_b64_e32 v[86:87], 0
	v_mov_b64_e32 v[88:89], 0
	v_mov_b64_e32 v[90:91], 0
	v_mov_b64_e32 v[92:93], 0
	v_mov_b64_e32 v[94:95], 0
	v_mov_b64_e32 v[96:97], 0
	v_mov_b64_e32 v[98:99], 0
	v_mov_b64_e32 v[100:101], 0
	v_mov_b64_e32 v[102:103], 0
	v_mov_b64_e32 v[104:105], 0
	v_mov_b64_e32 v[106:107], 0
	v_mov_b64_e32 v[108:109], 0
	v_mov_b64_e32 v[110:111], 0
	v_mov_b64_e32 v[112:113], 0
	v_mov_b64_e32 v[114:115], 0
	v_mov_b64_e32 v[116:117], 0
	v_mov_b64_e32 v[118:119], 0
	v_mov_b64_e32 v[120:121], 0
	v_mov_b64_e32 v[122:123], 0
	v_mov_b64_e32 v[124:125], 0
	v_mov_b64_e32 v[126:127], 0
	v_mov_b64_e32 v[128:129], 0

; template <class Epi, bool ALIGN_EPI>
; __device__ __forceinline__ void gemm_phase(LAS unsigned char* lds, const Gemm g, const StaticOrder S, const Epi E) {
;     ...
;     for (;;) {
;         const bool has_next = S.next(ui + 1, nxt);
;         const char* nA = has_next ? (const char*)g.A + (size_t)nxt.pm * tstepA + PG8_KOFS(nxt) : cA; const char* nB = has_next ? (const char*)g.Bt + (size_t)nxt.pn * tstepB + PG8_KOFS(nxt) : cB;
;     ...
; #pragma unroll
;         for (int a = 0; a < 2; ++a)
; #pragma unroll
;             for (int b = 0; b < 2; ++b)
; #pragma unroll
;                 for (int m = 0; m < 4; ++m)
; #pragma unroll
;                     for (int n = 0; n < 2; ++n) acc[a][b][m][n] = (f32x4){0.f, 0.f, 0.f, 0.f};
.LBB0_1814:
	s_ashr_i32 s47, s46, 31
	s_lshl_b64 s[0:1], s[46:47], 17
	v_readlane_b32 s12, v255, 37
	s_add_u32 s50, s12, s0
	v_readlane_b32 s0, v255, 38
	s_addc_u32 s51, s0, s1
	s_and_b64 s[0:1], s[42:43], exec
	v_mov_b32_e32 v0, 0
	s_cselect_b32 s47, s51, s53
	s_cselect_b32 s93, s50, s52
	s_mov_b64 s[64:65], 0
	s_mov_b64 s[42:43], -1
	s_mov_b64 s[62:63], 0
	v_mov_b32_e32 v1, 0
	v_mov_b64_e32 v[2:3], 0
	v_mov_b64_e32 v[4:5], 0
	v_mov_b64_e32 v[6:7], 0
	v_mov_b64_e32 v[8:9], 0
	v_mov_b64_e32 v[10:11], 0
	v_mov_b64_e32 v[12:13], 0
	v_mov_b64_e32 v[14:15], 0
	v_mov_b64_e32 v[16:17], 0
	v_mov_b64_e32 v[18:19], 0
	v_mov_b64_e32 v[20:21], 0
	v_mov_b64_e32 v[22:23], 0
	v_mov_b64_e32 v[24:25], 0
	v_mov_b64_e32 v[26:27], 0
	v_mov_b64_e32 v[28:29], 0
	v_mov_b64_e32 v[30:31], 0
	v_mov_b64_e32 v[32:33], 0
	v_mov_b64_e32 v[34:35], 0
	v_mov_b64_e32 v[36:37], 0
	v_mov_b64_e32 v[38:39], 0
	v_mov_b64_e32 v[40:41], 0
	v_mov_b64_e32 v[42:43], 0
	v_mov_b64_e32 v[44:45], 0
	v_mov_b64_e32 v[46:47], 0
	v_mov_b64_e32 v[48:49], 0
	v_mov_b64_e32 v[50:51], 0
	v_mov_b64_e32 v[52:53], 0
	v_mov_b64_e32 v[54:55], 0
	v_mov_b64_e32 v[56:57], 0
	v_mov_b64_e32 v[58:59], 0
	v_mov_b64_e32 v[60:61], 0
	v_mov_b64_e32 v[62:63], 0
	v_mov_b64_e32 v[64:65], 0
	v_mov_b64_e32 v[66:67], 0
	v_mov_b64_e32 v[68:69], 0
	v_mov_b64_e32 v[70:71], 0
	v_mov_b64_e32 v[72:73], 0
	v_mov_b64_e32 v[74:75], 0
	v_mov_b64_e32 v[76:77], 0
	v_mov_b64_e32 v[78:79], 0
	v_mov_b64_e32 v[82:83], 0
	v_mov_b64_e32 v[84:85], 0
	v_mov_b64_e32 v[86:87], 0
	v_mov_b64_e32 v[88:89], 0
	v_mov_b64_e32 v[90:91], 0
	v_mov_b64_e32 v[92:93], 0
	v_mov_b64_e32 v[94:95], 0
	v_mov_b64_e32 v[96:97], 0
	v_mov_b64_e32 v[98:99], 0
	v_mov_b64_e32 v[100:101], 0
	v_mov_b64_e32 v[102:103], 0
	v_mov_b64_e32 v[104:105], 0
	v_mov_b64_e32 v[106:107], 0
	v_mov_b64_e32 v[108:109], 0
	v_mov_b64_e32 v[110:111], 0
	v_mov_b64_e32 v[112:113], 0
	v_mov_b64_e32 v[114:115], 0
	v_mov_b64_e32 v[116:117], 0
	v_mov_b64_e32 v[118:119], 0
	v_mov_b64_e32 v[120:121], 0
	v_mov_b64_e32 v[122:123], 0
	v_mov_b64_e32 v[124:125], 0
	v_mov_b64_e32 v[126:127], 0
	v_mov_b64_e32 v[128:129], 0

; template <class Epi, bool ALIGN_EPI>
; __device__ __forceinline__ void gemm_phase(LAS unsigned char* lds, const Gemm g, const StaticOrder S, const Epi E) {
;     ...
;     for (;;) {
;         const bool has_next = S.next(ui + 1, nxt);
;         const char* nA = has_next ? (const char*)g.A + (size_t)nxt.pm * tstepA + PG8_KOFS(nxt) : cA; const char* nB = has_next ? (const char*)g.Bt + (size_t)nxt.pn * tstepB + PG8_KOFS(nxt) : cB;
;     ...
; #pragma unroll
;         for (int a = 0; a < 2; ++a)
; #pragma unroll
;             for (int b = 0; b < 2; ++b)
; #pragma unroll
;                 for (int m = 0; m < 4; ++m)
; #pragma unroll
;                     for (int n = 0; n < 2; ++n) acc[a][b][m][n] = (f32x4){0.f, 0.f, 0.f, 0.f};
.LBB0_2014:
	s_ashr_i32 s47, s46, 31
	s_lshl_b64 s[0:1], s[46:47], 19
	v_readlane_b32 s12, v255, 39
	s_add_u32 s50, s12, s0
	v_readlane_b32 s0, v255, 40
	s_addc_u32 s51, s0, s1
	s_and_b64 s[0:1], s[42:43], exec
	s_cselect_b32 s34, s51, s63
	s_cselect_b32 s35, s50, s62
	s_add_u32 s47, s62, 0x100
	v_mov_b32_e32 v0, 0
	s_addc_u32 s53, s63, 0
	s_mov_b32 s71, -2
	v_mov_b32_e32 v1, 0
	v_mov_b64_e32 v[2:3], 0
	v_mov_b64_e32 v[4:5], 0
	v_mov_b64_e32 v[6:7], 0
	v_mov_b64_e32 v[8:9], 0
	v_mov_b64_e32 v[10:11], 0
	v_mov_b64_e32 v[12:13], 0
	v_mov_b64_e32 v[14:15], 0
	v_mov_b64_e32 v[16:17], 0
	v_mov_b64_e32 v[18:19], 0
	v_mov_b64_e32 v[20:21], 0
	v_mov_b64_e32 v[22:23], 0
	v_mov_b64_e32 v[24:25], 0
	v_mov_b64_e32 v[26:27], 0
	v_mov_b64_e32 v[28:29], 0
	v_mov_b64_e32 v[30:31], 0
	v_mov_b64_e32 v[32:33], 0
	v_mov_b64_e32 v[34:35], 0
	v_mov_b64_e32 v[36:37], 0
	v_mov_b64_e32 v[38:39], 0
	v_mov_b64_e32 v[40:41], 0
	v_mov_b64_e32 v[42:43], 0
	v_mov_b64_e32 v[44:45], 0
	v_mov_b64_e32 v[46:47], 0
	v_mov_b64_e32 v[48:49], 0
	v_mov_b64_e32 v[50:51], 0
	v_mov_b64_e32 v[52:53], 0
	v_mov_b64_e32 v[54:55], 0
	v_mov_b64_e32 v[56:57], 0
	v_mov_b64_e32 v[58:59], 0
	v_mov_b64_e32 v[60:61], 0
	v_mov_b64_e32 v[62:63], 0
	v_mov_b64_e32 v[64:65], 0
	v_mov_b64_e32 v[66:67], 0
	v_mov_b64_e32 v[68:69], 0
	v_mov_b64_e32 v[70:71], 0
	v_mov_b64_e32 v[72:73], 0
	v_mov_b64_e32 v[74:75], 0
	v_mov_b64_e32 v[76:77], 0
	v_mov_b64_e32 v[78:79], 0
	v_mov_b64_e32 v[82:83], 0
	v_mov_b64_e32 v[84:85], 0
	v_mov_b64_e32 v[86:87], 0
	v_mov_b64_e32 v[88:89], 0
	v_mov_b64_e32 v[90:91], 0
	v_mov_b64_e32 v[92:93], 0
	v_mov_b64_e32 v[94:95], 0
	v_mov_b64_e32 v[96:97], 0
	v_mov_b64_e32 v[98:99], 0
	v_mov_b64_e32 v[100:101], 0
	v_mov_b64_e32 v[102:103], 0
	v_mov_b64_e32 v[104:105], 0
	v_mov_b64_e32 v[106:107], 0
	v_mov_b64_e32 v[108:109], 0
	v_mov_b64_e32 v[110:111], 0
	v_mov_b64_e32 v[112:113], 0
	v_mov_b64_e32 v[114:115], 0
	v_mov_b64_e32 v[116:117], 0
	v_mov_b64_e32 v[118:119], 0
	v_mov_b64_e32 v[120:121], 0
	v_mov_b64_e32 v[122:123], 0
	v_mov_b64_e32 v[124:125], 0
	v_mov_b64_e32 v[126:127], 0
	v_mov_b64_e32 v[128:129], 0
